# PRO_C XS row loop: a row's 8 x and 8 scale chunks requested at the top of the row, gains loaded once before the loop, counted in-order waits (was 8 serial 3-load round trips per row); on top of v58
# speedup vs baseline: 1.0067x; 1.0024x over previous
; __device__ __forceinline__ void pro_c(LAS unsigned char* lds, const float* const* in, unsigned char* wsl, int cid, int G, int tid) {
;     ...
;     for (int row = cid * 8 + wave; row < M; row += G * 8) { const int b = row / SEQ;
;         const float* xr = in[0] + (size_t)row * D; bf16_t* xs = (bf16_t*)(wsl + O_XS); float* rss = (float*)(wsl + O_RSS1) + (size_t)row * 32;
; #pragma unroll
;         for (int j = 0; j < 8; ++j) { const int c = 4 * lane + 256 * j; const f32x4 v = __builtin_nontemporal_load((const f32x4*)(xr + c));
.LBB0_234:
	v_readlane_b32 s12, v254, 30
	s_cmpk_gt_i32 s6, 0x3fff
	v_readlane_b32 s13, v254, 31
	v_readlane_b32 s20, v254, 38
	v_readlane_b32 s21, v254, 39
	v_readlane_b32 s40, v254, 14
	s_mov_b32 s63, s74
	v_readlane_b32 s14, v254, 32
	v_readlane_b32 s15, v254, 33
	v_readlane_b32 s16, v254, 34
	v_readlane_b32 s17, v254, 35
	v_readlane_b32 s18, v254, 36
	v_readlane_b32 s19, v254, 37
	v_readlane_b32 s22, v254, 40
	v_readlane_b32 s23, v254, 41
	v_readlane_b32 s24, v254, 42
	v_readlane_b32 s25, v254, 43
	v_readlane_b32 s26, v254, 44
	v_readlane_b32 s27, v254, 45
	v_readlane_b32 s41, v254, 15
	v_readlane_b32 s42, v254, 16
	v_readlane_b32 s43, v254, 17
	v_readlane_b32 s44, v254, 18
	v_readlane_b32 s45, v254, 19
	v_readlane_b32 s46, v254, 20
	v_readlane_b32 s47, v254, 21
	v_readlane_b32 s48, v254, 22
	v_readlane_b32 s49, v254, 23
	v_readlane_b32 s50, v254, 24
	v_readlane_b32 s51, v254, 25
	v_readlane_b32 s52, v254, 26
	v_readlane_b32 s53, v254, 27
	v_readlane_b32 s54, v254, 28
	v_readlane_b32 s55, v254, 29
	s_cbranch_scc1 .LBB0_253
	v_and_b32_e32 v0, 15, v53
	v_cmp_eq_u32_e32 vcc, 0, v0
	v_lshlrev_b32_e32 v0, 10, v55
	v_or_b32_e32 v18, 0x100, v52
	v_and_b32_e32 v16, 0xc000, v0
	v_lshlrev_b32_e32 v0, 8, v18
	v_or_b32_e32 v22, 0x200, v52
	v_and_b32_e32 v20, 0x1c000, v0
	v_lshlrev_b32_e32 v0, 8, v22
	v_or_b32_e32 v26, 0x300, v52
	v_and_b32_e32 v24, 0x2c000, v0
	v_lshlrev_b32_e32 v0, 8, v26
	v_or_b32_e32 v30, 0x400, v52
	s_add_u32 s3, s3, 0x20104000
	v_and_b32_e32 v28, 0x3c000, v0
	v_lshlrev_b32_e32 v0, 8, v30
	v_or_b32_e32 v44, 0x500, v52
	s_addc_u32 s16, s33, 0
	v_and_b32_e32 v32, 0x4c000, v0
	v_lshlrev_b32_e32 v0, 8, v44
	v_or_b32_e32 v48, 0x600, v52
	s_lshl_b32 s1, s7, 6
	s_ashr_i32 s7, s6, 31
	s_lshl_b32 s0, s38, 3
	v_and_b32_e32 v46, 0x5c000, v0
	v_lshlrev_b32_e32 v0, 8, v48
	v_or_b32_e32 v54, 0x700, v52
	s_add_i32 s2, s2, s1
	s_lshl_b32 s17, s38, 9
	s_lshl_b64 s[10:11], s[6:7], 13
	v_and_b32_e32 v50, 0x6c000, v0
	v_lshlrev_b32_e32 v0, 8, v54
	s_add_u32 s10, s12, s10
	s_waitcnt lgkmcnt(0)
	v_mov_b32_e32 v1, 0
	v_and_b32_e32 v56, 0x7c000, v0
	v_lshlrev_b32_e32 v0, 4, v55
	s_addc_u32 s11, s13, s11
	v_lshl_add_u64 v[12:13], s[10:11], 0, v[0:1]
	s_mov_b64 s[10:11], 0x1000
	s_ashr_i32 s1, s0, 31
	v_lshlrev_b32_e32 v4, 2, v30
	v_mov_b32_e32 v5, v1
	v_lshlrev_b32_e32 v6, 2, v44
	v_mov_b32_e32 v7, v1
	v_lshlrev_b32_e32 v8, 2, v48
	v_mov_b32_e32 v9, v1
	v_lshlrev_b32_e32 v10, 2, v54
	v_mov_b32_e32 v11, v1
	v_lshl_add_u64 v[12:13], v[12:13], 0, s[10:11]
	s_lshl_b64 s[10:11], s[0:1], 13
	s_lshl_b64 s[12:13], s[6:7], 7
	v_lshl_add_u64 v[2:3], s[20:21], 0, v[0:1]
	v_lshl_add_u64 v[4:5], s[20:21], 0, v[4:5]
	v_lshl_add_u64 v[6:7], s[20:21], 0, v[6:7]
	v_lshl_add_u64 v[8:9], s[20:21], 0, v[8:9]
	v_lshl_add_u64 v[10:11], s[20:21], 0, v[10:11]
	s_add_u32 s7, s8, s12
	v_readlane_b32 s20, v254, 0
	s_addc_u32 s9, s9, s13
	v_readlane_b32 s24, v254, 4
	v_lshrrev_b32_e32 v0, 2, v55
	v_readlane_b32 s25, v254, 5
	s_add_u32 s8, s24, s7
	v_and_b32_e32 v0, 12, v0
	s_addc_u32 s9, s25, s9
	v_lshl_add_u64 v[14:15], s[8:9], 0, v[0:1]
	s_mov_b64 s[8:9], 0x304040
	v_and_b32_e32 v34, 28, v52
	v_and_b32_e32 v62, 32, v52
	v_lshl_or_b32 v34, v62, 4, v34
	v_xor_b32_e32 v35, 4, v52
	v_xor_b32_e32 v36, 8, v52
	v_xor_b32_e32 v37, 16, v52
	v_xor_b32_e32 v38, 32, v52
	v_lshl_add_u64 v[14:15], v[14:15], 0, s[8:9]
	s_lshl_b64 s[8:9], s[0:1], 7
	v_lshlrev_b32_e32 v39, 2, v52
	v_lshlrev_b32_e32 v16, 1, v16
	v_lshlrev_b32_e32 v40, 2, v18
	v_lshlrev_b32_e32 v18, 1, v20
	v_lshlrev_b32_e32 v41, 2, v22
	v_lshlrev_b32_e32 v20, 1, v24
	v_lshlrev_b32_e32 v42, 2, v26
	v_lshlrev_b32_e32 v22, 1, v28
	v_lshlrev_b32_e32 v43, 2, v30
	v_lshlrev_b32_e32 v24, 1, v32
	v_lshlrev_b32_e32 v44, 2, v44
	v_lshlrev_b32_e32 v26, 1, v46
	v_lshlrev_b32_e32 v45, 2, v48
	v_lshlrev_b32_e32 v28, 1, v50
	v_lshlrev_b32_e32 v46, 2, v54
	v_lshlrev_b32_e32 v30, 1, v56
	v_mov_b32_e32 v17, v1
	v_readlane_b32 s21, v254, 1
	v_readlane_b32 s22, v254, 2
	v_readlane_b32 s23, v254, 3
	v_readlane_b32 s26, v254, 6
	v_readlane_b32 s27, v254, 7
	global_load_dwordx4 v[130:133], v[2:3], off
	global_load_dwordx4 v[134:137], v[2:3], off offset:1024
	global_load_dwordx4 v[138:141], v[2:3], off offset:2048
	global_load_dwordx4 v[142:145], v[2:3], off offset:3072
	global_load_dwordx4 v[146:149], v[4:5], off
	global_load_dwordx4 v[150:153], v[6:7], off
	global_load_dwordx4 v[154:157], v[8:9], off
	global_load_dwordx4 v[158:161], v[10:11], off
	s_waitcnt vmcnt(0)
	s_branch .LBB0_237

; __device__ __forceinline__ unsigned cvt_pk_bf16_c(float lo, float hi) { const f32x2_t v = {lo, hi}; return __builtin_bit_cast(unsigned, __builtin_convertvector(v, bf16x2_t)); }
; __device__ __forceinline__ float bperm(float v, int src_lane) { return __int_as_float(__builtin_amdgcn_ds_bpermute(src_lane << 2, __float_as_int(v))); }
; __host__ __device__ __forceinline__ size_t xs_off(int row, int col) { return (size_t)(row >> 8) * (256 * D) + (size_t)(col >> 6) * (256 * 64) + (size_t)((row & 255) * 64 + (col & 63)); }
; __device__ __forceinline__ void pro_c(LAS unsigned char* lds, const float* const* in, unsigned char* wsl, int cid, int G, int tid) {
;     ...
;         for (int j = 0; j < 8; ++j) { const int c = 4 * lane + 256 * j; const f32x4 v = __builtin_nontemporal_load((const f32x4*)(xr + c));
;             const f32x4 g = *(const f32x4*)(in[4] + c), sc = *(const f32x4*)(MOD + (size_t)b * 6 * D + D + c);
;             u32x2 o; o.x = cvt_pk_bf16_c(v.x * (g.x * (1.f + sc.x)), v.y * (g.y * (1.f + sc.y))); o.y = cvt_pk_bf16_c(v.z * (g.z * (1.f + sc.z)), v.w * (g.w * (1.f + sc.w)));
;             *(u32x2*)(xs + xs_off(row, c)) = o;
;             float ss = (v.x * v.x + v.y * v.y) + (v.z * v.z + v.w * v.w);
;             ss += bperm(ss, lane ^ 1); ss += bperm(ss, lane ^ 2); ss += bperm(ss, lane ^ 4); ss += bperm(ss, lane ^ 8);
;             if ((lane & 15) == 0) rss[4 * j + (lane >> 4)] = ss; }
.LBB0_237:
	global_load_dwordx4 v[194:197], v[12:13], off offset:-4096 nt
	s_ashr_i32 s1, s6, 31
	s_lshr_b32 s1, s1, 20
	s_add_i32 s1, s6, s1
	s_ashr_i32 s1, s1, 12
	s_mul_i32 s12, s1, 6
	s_ashr_i32 s13, s12, 31
	s_lshl_b64 s[12:13], s[12:13], 13
	s_add_u32 s1, s4, s12
	s_addc_u32 s7, s5, s13
	s_add_u32 s12, s1, 0x2000
	s_addc_u32 s13, s7, 0
	global_load_dwordx4 v[198:201], v[12:13], off offset:-3072 nt
	global_load_dwordx4 v[202:205], v[12:13], off offset:-2048 nt
	global_load_dwordx4 v[206:209], v[12:13], off offset:-1024 nt
	global_load_dwordx4 v[210:213], v[12:13], off nt
	global_load_dwordx4 v[214:217], v[12:13], off offset:1024 nt
	global_load_dwordx4 v[222:225], v[12:13], off offset:2048 nt
	global_load_dwordx4 v[226:229], v[12:13], off offset:3072 nt
	global_load_dwordx4 v[162:165], v39, s[12:13]
	global_load_dwordx4 v[166:169], v40, s[12:13]
	global_load_dwordx4 v[170:173], v41, s[12:13]
	global_load_dwordx4 v[174:177], v42, s[12:13]
	global_load_dwordx4 v[178:181], v43, s[12:13]
	global_load_dwordx4 v[182:185], v44, s[12:13]
	global_load_dwordx4 v[186:189], v45, s[12:13]
	global_load_dwordx4 v[190:193], v46, s[12:13]
	s_ashr_i32 s14, s6, 8
	s_ashr_i32 s15, s14, 31
	s_and_b32 s1, s2, 0x3fc0
	s_and_b32 s100, s1, 0x3c0
	s_lshr_b32 s100, s100, 1
	s_and_b32 s1, s1, 0x3c00
	s_or_b32 s1, s1, s100
	s_lshl_b64 s[14:15], s[14:15], 20
	v_or_b32_e32 v21, s1, v34
	s_add_u32 s14, s3, s14
	s_addc_u32 s15, s16, s15
	s_waitcnt vmcnt(15)
	v_mul_f32_e32 v0, v195, v195
	s_waitcnt lgkmcnt(0)
	v_mul_f32_e32 v19, v197, v197
	v_fmac_f32_e32 v0, v194, v194
	v_fmac_f32_e32 v19, v196, v196
	v_add_f32_e32 v0, v0, v19
	ds_bpermute_b32 v19, v35, v0
	s_waitcnt lgkmcnt(0)
	v_add_f32_e32 v19, v0, v19
	ds_bpermute_b32 v23, v36, v19
	v_lshlrev_b32_e32 v0, 1, v21
	v_lshl_add_u64 v[32:33], s[14:15], 0, v[0:1]
	s_waitcnt vmcnt(7)
	v_pk_add_f32 v[52:53], v[162:163], 1.0 op_sel_hi:[1,0]
	s_waitcnt lgkmcnt(0)
	v_add_f32_e32 v0, v19, v23
	ds_bpermute_b32 v19, v37, v0
	v_pk_mul_f32 v[52:53], v[130:131], v[52:53]
	s_waitcnt lgkmcnt(0)
	v_add_f32_e32 v0, v0, v19
	ds_bpermute_b32 v19, v38, v0
	v_pk_mul_f32 v[48:49], v[194:195], v[52:53]
	v_pk_add_f32 v[52:53], v[164:165], 1.0 op_sel_hi:[1,0]
	v_cvt_pk_bf16_f32 v48, v48, v49
	v_pk_mul_f32 v[52:53], v[132:133], v[52:53]
	s_nop 0
	v_pk_mul_f32 v[50:51], v[196:197], v[52:53]
	s_nop 0
	v_cvt_pk_bf16_f32 v49, v50, v51
	v_lshl_add_u64 v[50:51], v[32:33], 0, v[16:17]
	global_store_dwordx2 v[50:51], v[48:49], off
	s_and_saveexec_b64 s[14:15], vcc
	s_cbranch_execz .LBB0_239
	s_waitcnt lgkmcnt(0)
	v_add_f32_e32 v0, v0, v19
	global_store_dword v[14:15], v0, off offset:-64
.LBB0_239:
	s_or_b64 exec, exec, s[14:15]
	s_waitcnt vmcnt(15)
	v_mul_f32_e32 v0, v199, v199
	s_waitcnt lgkmcnt(0)
	v_mul_f32_e32 v19, v201, v201
	v_fmac_f32_e32 v0, v198, v198
	v_fmac_f32_e32 v19, v200, v200
	v_add_f32_e32 v0, v0, v19
	ds_bpermute_b32 v19, v35, v0
	s_waitcnt vmcnt(7)
	v_pk_add_f32 v[52:53], v[166:167], 1.0 op_sel_hi:[1,0]
	s_waitcnt lgkmcnt(0)
	v_add_f32_e32 v0, v0, v19
	ds_bpermute_b32 v19, v36, v0
	v_pk_mul_f32 v[52:53], v[134:135], v[52:53]
	s_waitcnt lgkmcnt(0)
	v_add_f32_e32 v0, v0, v19
	ds_bpermute_b32 v19, v37, v0
	v_pk_mul_f32 v[48:49], v[198:199], v[52:53]
	v_pk_add_f32 v[52:53], v[168:169], 1.0 op_sel_hi:[1,0]
	v_cvt_pk_bf16_f32 v48, v48, v49
	v_pk_mul_f32 v[52:53], v[136:137], v[52:53]
	s_waitcnt lgkmcnt(0)
	v_add_f32_e32 v0, v0, v19
	ds_bpermute_b32 v21, v38, v0
	v_pk_mul_f32 v[50:51], v[200:201], v[52:53]
	v_mov_b32_e32 v19, v1
	v_cvt_pk_bf16_f32 v49, v50, v51
	v_lshl_add_u64 v[50:51], v[32:33], 0, v[18:19]
	global_store_dwordx2 v[50:51], v[48:49], off
	s_and_saveexec_b64 s[14:15], vcc
	s_cbranch_execz .LBB0_241
	s_waitcnt lgkmcnt(0)
	v_add_f32_e32 v0, v0, v21
	global_store_dword v[14:15], v0, off offset:-48
.LBB0_241:
	s_or_b64 exec, exec, s[14:15]
	s_waitcnt lgkmcnt(0)
	v_mov_b32_e32 v21, v1
	s_waitcnt vmcnt(15)
	v_mul_f32_e32 v0, v203, v203
	v_mul_f32_e32 v19, v205, v205
	v_fmac_f32_e32 v0, v202, v202
	v_fmac_f32_e32 v19, v204, v204
	v_add_f32_e32 v0, v0, v19
	ds_bpermute_b32 v19, v35, v0
	s_waitcnt vmcnt(7)
	v_pk_add_f32 v[52:53], v[170:171], 1.0 op_sel_hi:[1,0]
	s_waitcnt lgkmcnt(0)
	v_add_f32_e32 v0, v0, v19
	ds_bpermute_b32 v19, v36, v0
	v_pk_mul_f32 v[52:53], v[138:139], v[52:53]
	s_waitcnt lgkmcnt(0)
	v_add_f32_e32 v0, v0, v19
	ds_bpermute_b32 v19, v37, v0
	v_pk_mul_f32 v[48:49], v[202:203], v[52:53]
	v_pk_add_f32 v[52:53], v[172:173], 1.0 op_sel_hi:[1,0]
	v_cvt_pk_bf16_f32 v48, v48, v49
	v_pk_mul_f32 v[52:53], v[140:141], v[52:53]
	s_waitcnt lgkmcnt(0)
	v_add_f32_e32 v0, v0, v19
	ds_bpermute_b32 v19, v38, v0
	v_pk_mul_f32 v[50:51], v[204:205], v[52:53]
	s_nop 0
	v_cvt_pk_bf16_f32 v49, v50, v51
	v_lshl_add_u64 v[50:51], v[32:33], 0, v[20:21]
	global_store_dwordx2 v[50:51], v[48:49], off
	s_and_saveexec_b64 s[14:15], vcc
	s_cbranch_execz .LBB0_243
	s_waitcnt lgkmcnt(0)
	v_add_f32_e32 v0, v0, v19
	global_store_dword v[14:15], v0, off offset:-32
; __device__ __forceinline__ unsigned cvt_pk_bf16_c(float lo, float hi) { const f32x2_t v = {lo, hi}; return __builtin_bit_cast(unsigned, __builtin_convertvector(v, bf16x2_t)); }
; __device__ __forceinline__ float bperm(float v, int src_lane) { return __int_as_float(__builtin_amdgcn_ds_bpermute(src_lane << 2, __float_as_int(v))); }
; __host__ __device__ __forceinline__ size_t xs_off(int row, int col) { return (size_t)(row >> 8) * (256 * D) + (size_t)(col >> 6) * (256 * 64) + (size_t)((row & 255) * 64 + (col & 63)); }
; __device__ __forceinline__ void pro_c(LAS unsigned char* lds, const float* const* in, unsigned char* wsl, int cid, int G, int tid) {
;     ...
;         for (int j = 0; j < 8; ++j) { const int c = 4 * lane + 256 * j; const f32x4 v = __builtin_nontemporal_load((const f32x4*)(xr + c));
;             const f32x4 g = *(const f32x4*)(in[4] + c), sc = *(const f32x4*)(MOD + (size_t)b * 6 * D + D + c);
;             u32x2 o; o.x = cvt_pk_bf16_c(v.x * (g.x * (1.f + sc.x)), v.y * (g.y * (1.f + sc.y))); o.y = cvt_pk_bf16_c(v.z * (g.z * (1.f + sc.z)), v.w * (g.w * (1.f + sc.w)));
;             *(u32x2*)(xs + xs_off(row, c)) = o;
;             float ss = (v.x * v.x + v.y * v.y) + (v.z * v.z + v.w * v.w);
;             ss += bperm(ss, lane ^ 1); ss += bperm(ss, lane ^ 2); ss += bperm(ss, lane ^ 4); ss += bperm(ss, lane ^ 8);
;             if ((lane & 15) == 0) rss[4 * j + (lane >> 4)] = ss; }
.LBB0_243:
	s_or_b64 exec, exec, s[14:15]
	v_mov_b32_e32 v23, v1
	s_waitcnt vmcnt(15)
	v_mul_f32_e32 v0, v207, v207
	s_waitcnt lgkmcnt(0)
	v_mul_f32_e32 v19, v209, v209
	v_fmac_f32_e32 v0, v206, v206
	v_fmac_f32_e32 v19, v208, v208
	v_add_f32_e32 v0, v0, v19
	ds_bpermute_b32 v19, v35, v0
	s_waitcnt vmcnt(7)
	v_pk_add_f32 v[52:53], v[174:175], 1.0 op_sel_hi:[1,0]
	s_waitcnt lgkmcnt(0)
	v_add_f32_e32 v0, v0, v19
	ds_bpermute_b32 v19, v36, v0
	v_pk_mul_f32 v[52:53], v[142:143], v[52:53]
	s_waitcnt lgkmcnt(0)
	v_add_f32_e32 v0, v0, v19
	ds_bpermute_b32 v19, v37, v0
	v_pk_mul_f32 v[48:49], v[206:207], v[52:53]
	v_pk_add_f32 v[52:53], v[176:177], 1.0 op_sel_hi:[1,0]
	v_cvt_pk_bf16_f32 v48, v48, v49
	v_pk_mul_f32 v[52:53], v[144:145], v[52:53]
	s_waitcnt lgkmcnt(0)
	v_add_f32_e32 v0, v0, v19
	ds_bpermute_b32 v19, v38, v0
	v_pk_mul_f32 v[50:51], v[208:209], v[52:53]
	s_nop 0
	v_cvt_pk_bf16_f32 v49, v50, v51
	v_lshl_add_u64 v[50:51], v[32:33], 0, v[22:23]
	global_store_dwordx2 v[50:51], v[48:49], off
	s_and_saveexec_b64 s[14:15], vcc
	s_cbranch_execz .LBB0_245
	s_waitcnt lgkmcnt(0)
	v_add_f32_e32 v0, v0, v19
	global_store_dword v[14:15], v0, off offset:-16
.LBB0_245:
	s_or_b64 exec, exec, s[14:15]
	v_mov_b32_e32 v25, v1
	s_waitcnt vmcnt(15)
	v_mul_f32_e32 v0, v211, v211
	s_waitcnt lgkmcnt(0)
	v_mul_f32_e32 v19, v213, v213
	v_fmac_f32_e32 v0, v210, v210
	v_fmac_f32_e32 v19, v212, v212
	v_add_f32_e32 v0, v0, v19
	ds_bpermute_b32 v19, v35, v0
	s_waitcnt vmcnt(7)
	v_pk_add_f32 v[52:53], v[178:179], 1.0 op_sel_hi:[1,0]
	s_waitcnt lgkmcnt(0)
	v_add_f32_e32 v0, v0, v19
	ds_bpermute_b32 v19, v36, v0
	v_pk_mul_f32 v[52:53], v[146:147], v[52:53]
	s_waitcnt lgkmcnt(0)
	v_add_f32_e32 v0, v0, v19
	ds_bpermute_b32 v19, v37, v0
	v_pk_mul_f32 v[48:49], v[210:211], v[52:53]
	v_pk_add_f32 v[52:53], v[180:181], 1.0 op_sel_hi:[1,0]
	v_cvt_pk_bf16_f32 v48, v48, v49
	v_pk_mul_f32 v[52:53], v[148:149], v[52:53]
	s_waitcnt lgkmcnt(0)
	v_add_f32_e32 v0, v0, v19
	ds_bpermute_b32 v19, v38, v0
	v_pk_mul_f32 v[50:51], v[212:213], v[52:53]
	s_nop 0
	v_cvt_pk_bf16_f32 v49, v50, v51
	v_lshl_add_u64 v[50:51], v[32:33], 0, v[24:25]
	global_store_dwordx2 v[50:51], v[48:49], off
	s_and_saveexec_b64 s[14:15], vcc
	s_cbranch_execz .LBB0_247
	s_waitcnt lgkmcnt(0)
	v_add_f32_e32 v0, v0, v19
	global_store_dword v[14:15], v0, off
.LBB0_247:
	s_or_b64 exec, exec, s[14:15]
	v_mov_b32_e32 v27, v1
	s_waitcnt vmcnt(15)
	v_mul_f32_e32 v0, v215, v215
	s_waitcnt lgkmcnt(0)
	v_mul_f32_e32 v19, v217, v217
	v_fmac_f32_e32 v0, v214, v214
	v_fmac_f32_e32 v19, v216, v216
	v_add_f32_e32 v0, v0, v19
	ds_bpermute_b32 v19, v35, v0
	s_waitcnt vmcnt(7)
	v_pk_add_f32 v[52:53], v[182:183], 1.0 op_sel_hi:[1,0]
	s_waitcnt lgkmcnt(0)
	v_add_f32_e32 v0, v0, v19
	ds_bpermute_b32 v19, v36, v0
	v_pk_mul_f32 v[52:53], v[150:151], v[52:53]
	s_waitcnt lgkmcnt(0)
	v_add_f32_e32 v0, v0, v19
	ds_bpermute_b32 v19, v37, v0
	v_pk_mul_f32 v[48:49], v[214:215], v[52:53]
	v_pk_add_f32 v[52:53], v[184:185], 1.0 op_sel_hi:[1,0]
	v_cvt_pk_bf16_f32 v48, v48, v49
	v_pk_mul_f32 v[52:53], v[152:153], v[52:53]
	s_waitcnt lgkmcnt(0)
	v_add_f32_e32 v0, v0, v19
	ds_bpermute_b32 v19, v38, v0
	v_pk_mul_f32 v[50:51], v[216:217], v[52:53]
	s_nop 0
	v_cvt_pk_bf16_f32 v49, v50, v51
	v_lshl_add_u64 v[50:51], v[32:33], 0, v[26:27]
	global_store_dwordx2 v[50:51], v[48:49], off
	s_and_saveexec_b64 s[14:15], vcc
	s_cbranch_execz .LBB0_249
	s_waitcnt lgkmcnt(0)
	v_add_f32_e32 v0, v0, v19
	global_store_dword v[14:15], v0, off offset:16
.LBB0_249:
	s_or_b64 exec, exec, s[14:15]
	v_mov_b32_e32 v29, v1
	s_waitcnt vmcnt(15)
	v_mul_f32_e32 v0, v223, v223
	s_waitcnt lgkmcnt(0)
	v_mul_f32_e32 v19, v225, v225
	v_fmac_f32_e32 v0, v222, v222
	v_fmac_f32_e32 v19, v224, v224
	v_add_f32_e32 v0, v0, v19
	ds_bpermute_b32 v19, v35, v0
	s_waitcnt vmcnt(7)
	v_pk_add_f32 v[52:53], v[186:187], 1.0 op_sel_hi:[1,0]
	s_waitcnt lgkmcnt(0)
	v_add_f32_e32 v0, v0, v19
	ds_bpermute_b32 v19, v36, v0
	v_pk_mul_f32 v[52:53], v[154:155], v[52:53]
	s_waitcnt lgkmcnt(0)
	v_add_f32_e32 v0, v0, v19
	ds_bpermute_b32 v19, v37, v0
	v_pk_mul_f32 v[48:49], v[222:223], v[52:53]
	v_pk_add_f32 v[52:53], v[188:189], 1.0 op_sel_hi:[1,0]
	v_cvt_pk_bf16_f32 v48, v48, v49
	v_pk_mul_f32 v[52:53], v[156:157], v[52:53]
	s_waitcnt lgkmcnt(0)
	v_add_f32_e32 v0, v0, v19
	ds_bpermute_b32 v19, v38, v0
	v_pk_mul_f32 v[50:51], v[224:225], v[52:53]
	s_nop 0
	v_cvt_pk_bf16_f32 v49, v50, v51
	v_lshl_add_u64 v[50:51], v[32:33], 0, v[28:29]
	global_store_dwordx2 v[50:51], v[48:49], off
	s_and_saveexec_b64 s[14:15], vcc
	s_cbranch_execz .LBB0_251
	s_waitcnt lgkmcnt(0)
	v_add_f32_e32 v0, v0, v19
	global_store_dword v[14:15], v0, off offset:32
.LBB0_251:
	s_or_b64 exec, exec, s[14:15]
	v_mov_b32_e32 v31, v1
	v_lshl_add_u64 v[32:33], v[32:33], 0, v[30:31]
	s_waitcnt vmcnt(15)
	v_mul_f32_e32 v0, v227, v227
	s_waitcnt lgkmcnt(0)
	v_mul_f32_e32 v19, v229, v229
	v_fmac_f32_e32 v0, v226, v226
	v_fmac_f32_e32 v19, v228, v228
	v_add_f32_e32 v0, v0, v19
	ds_bpermute_b32 v19, v35, v0
	s_waitcnt vmcnt(7)
	v_pk_add_f32 v[52:53], v[190:191], 1.0 op_sel_hi:[1,0]
	s_waitcnt lgkmcnt(0)
	v_add_f32_e32 v0, v0, v19
	ds_bpermute_b32 v19, v36, v0
	v_pk_mul_f32 v[52:53], v[158:159], v[52:53]
	s_waitcnt lgkmcnt(0)
	v_add_f32_e32 v0, v0, v19
	ds_bpermute_b32 v19, v37, v0
	v_pk_mul_f32 v[48:49], v[226:227], v[52:53]
	v_pk_add_f32 v[52:53], v[192:193], 1.0 op_sel_hi:[1,0]
	v_cvt_pk_bf16_f32 v48, v48, v49
	v_pk_mul_f32 v[52:53], v[160:161], v[52:53]
	s_waitcnt lgkmcnt(0)
	v_add_f32_e32 v0, v0, v19
	ds_bpermute_b32 v19, v38, v0
	v_pk_mul_f32 v[50:51], v[228:229], v[52:53]
	s_nop 0
	v_cvt_pk_bf16_f32 v49, v50, v51
	global_store_dwordx2 v[32:33], v[48:49], off
	s_and_saveexec_b64 s[12:13], vcc
	s_cbranch_execz .LBB0_236
	s_waitcnt lgkmcnt(0)
	v_add_f32_e32 v0, v0, v19
	global_store_dword v[14:15], v0, off offset:48
	s_branch .LBB0_236
